# attention K tile LDS layout: 128-byte halves swapped for rows with bit 3 set, so K-fragment ds_read_b128 lane groups cover all 64 banks (was two-way conflicted)
# speedup vs baseline: 1.0041x; 1.0011x over previous
.LBB0_1098:
	s_xor_b64 s[30:31], s[0:1], -1
	s_and_b64 s[0:1], s[0:1], exec
	s_cselect_b32 s1, s19, s37
	v_mov_b32_e32 v174, v190
	s_lshl_b32 s14, s1, 15
	s_lshl_b32 s0, s1, 16
	s_add_u32 s4, s16, s0
	v_readfirstlane_b32 s7, v174
	s_addc_u32 s5, s17, 0
	s_ashr_i32 s0, s7, 6
	v_lshlrev_b32_e32 v1, 3, v174
	s_lshl_b32 s6, s1, 8
	s_lshl_b32 s38, s1, 2
	s_ashr_i32 s1, s0, 31
	v_ashrrev_i32_e32 v0, 4, v174
	v_and_b32_e32 v2, 0x78, v1
	v_and_b32_e32 v175, 31, v174
	v_bfe_u32 v176, v174, 5, 1
	s_lshl_b32 s39, s0, 5
	s_and_b32 s7, s7, 0x3fffffc0
	s_lshl_b64 s[28:29], s[0:1], 13
	v_lshlrev_b32_e32 v2, 1, v2
	v_lshlrev_b32_e32 v3, 8, v0
	v_lshlrev_b32_e32 v10, 8, v175
	v_lshlrev_b32_e32 v11, 4, v176
	s_add_u32 s0, s4, s28
	v_or_b32_e32 v148, v2, v3
	v_or_b32_e32 v12, v11, v10
	s_addc_u32 s1, s5, s29
	global_load_dwordx4 v[96:99], v148, s[22:23]
	global_load_dwordx4 v[100:103], v148, s[20:21]
	global_load_dwordx4 v[136:139], v148, s[42:43]
	global_load_dwordx4 v[140:143], v148, s[26:27]
	global_load_dwordx4 v[104:107], v12, s[0:1]
	global_load_dwordx4 v[108:111], v12, s[0:1] offset:32
	global_load_dwordx4 v[112:115], v12, s[0:1] offset:64
	global_load_dwordx4 v[116:119], v12, s[0:1] offset:96
	global_load_dwordx4 v[120:123], v12, s[0:1] offset:128
	global_load_dwordx4 v[124:127], v12, s[0:1] offset:160
	global_load_dwordx4 v[128:131], v12, s[0:1] offset:192
	global_load_dwordx4 v[132:135], v12, s[0:1] offset:224
	v_and_b32_e32 v6, 0xfffff0, v0
	v_lshlrev_b32_e32 v7, 1, v0
	v_and_or_b32 v6, v7, 8, v6
	v_lshrrev_b32_e32 v7, 1, v0
	v_and_b32_e32 v8, 3, v0
	v_add_u32_e32 v0, 32, v0
	v_and_b32_e32 v4, 63, v174
	v_and_b32_e32 v9, 0xfffff0, v0
	v_lshlrev_b32_e32 v0, 1, v0
	v_lshlrev_b32_e32 v12, 4, v174
	s_lshl_b32 s0, s7, 2
	v_and_or_b32 v0, v0, 8, v9
	v_lshlrev_b32_e32 v9, 3, v4
	v_and_b32_e32 v13, 0xc0, v12
	v_lshlrev_b32_e32 v14, 1, v174
	s_add_i32 s0, s0, 0
	v_lshlrev_b32_e32 v5, 2, v176
	v_and_or_b32 v13, v9, 24, v13
	v_and_b32_e32 v14, 32, v14
	v_and_b32_e32 v9, 0x100, v9
	s_add_i32 s18, s38, 4
	s_add_i32 s39, s39, s6
	s_add_i32 s4, s0, 0x10000
	v_lshrrev_b32_e32 v6, 1, v6
	v_bfe_u32 v1, v1, 5, 2
	v_lshrrev_b32_e32 v0, 1, v0
	v_or3_b32 v9, v13, v14, v9
	v_subrev_u32_e32 v13, s6, v5
	s_cmp_lg_u32 0, -1
	v_or_b32_e32 v6, v6, v1
	v_and_or_b32 v7, v7, 4, v8
	v_or_b32_e32 v0, v0, v1
	v_and_b32_e32 v1, 0x70, v174
	v_cvt_f32_i32_e32 v13, v13
	s_cselect_b32 s0, 0, 0
	v_lshlrev_b32_e32 v6, 9, v6
	v_lshlrev_b32_e32 v7, 6, v7
	v_and_b32_e32 v8, 48, v2
	v_lshlrev_b32_e32 v0, 9, v0
	v_bitop3_b32 v1, v2, v3, v1 bitop3:0xde
	v_add_u32_e32 v178, s0, v9
	s_movk_i32 s0, 0x70
	v_or3_b32 v0, v0, v7, v8
	v_or3_b32 v6, v6, v7, v8
	v_add_u32_e32 v182, 0, v1
	v_bfe_u32 v200, v174, 7, 1
	v_lshlrev_b32_e32 v200, 7, v200
	v_xor_b32_e32 v182, v182, v200
	v_and_b32_e32 v1, 0x70, v12
	v_bitop3_b32 v2, v11, v12, s0 bitop3:0x78
	s_movk_i32 s0, 0x60
	s_waitcnt vmcnt(0)
	v_add_u32_e32 v180, 0, v6
	v_add_u32_e32 v181, 0, v0
	v_add_u32_e32 v0, 0, v10
	v_bitop3_b32 v3, v11, v1, 32 bitop3:0x36
	v_bitop3_b32 v6, v11, v1, 64 bitop3:0x36
	v_bitop3_b32 v1, v11, v1, s0 bitop3:0x36
	v_cmp_gt_u32_e64 s[0:1], 32, v4
	v_or_b32_e32 v4, s39, v175
	v_mov_b32_e32 v32, v149
	v_mov_b32_e32 v33, v149
	v_mov_b32_e32 v46, v149
	v_mov_b32_e32 v47, v149
	v_mul_f32_e32 v179, v172, v13
	v_add_u32_e32 v177, s4, v11
	v_sub_u32_e32 v184, v4, v5
	v_mov_b32_e32 v34, v149
	v_mov_b32_e32 v35, v149
	v_mov_b32_e32 v36, v149
	v_mov_b32_e32 v37, v149
	v_mov_b32_e32 v38, v149
	v_mov_b32_e32 v39, v149
	v_mov_b32_e32 v40, v149
	v_mov_b32_e32 v41, v149
	v_mov_b32_e32 v42, v149
	v_mov_b32_e32 v43, v149
	v_mov_b32_e32 v44, v149
	v_mov_b32_e32 v45, v149
	v_add_u32_e32 v186, v0, v2
	v_add_u32_e32 v187, v0, v3
	v_add_u32_e32 v188, v0, v6
	v_add_u32_e32 v189, v0, v1
	v_bfe_u32 v200, v174, 3, 1
	v_lshlrev_b32_e32 v200, 7, v200
	v_xor_b32_e32 v186, v186, v200
	v_xor_b32_e32 v187, v187, v200
	v_xor_b32_e32 v188, v188, v200
	v_xor_b32_e32 v189, v189, v200
	v_mov_b64_e32 v[62:63], v[46:47]
	v_mov_b64_e32 v[16:17], v[32:33]
	v_mov_b64_e32 v[0:1], v[32:33]
	s_mov_b32 s12, 0
	v_lshl_add_u32 v183, v175, 2, s4
	v_mov_b32_e32 v203, 0xf149f2ca
	v_mov_b32_e32 v185, 0
	s_movk_i32 s13, 0x7f
	s_mov_b64 s[46:47], s[2:3]
	s_mov_b64 s[40:41], s[24:25]
	v_mov_b64_e32 v[60:61], v[44:45]
	v_mov_b64_e32 v[58:59], v[42:43]
	v_mov_b64_e32 v[56:57], v[40:41]
	v_mov_b64_e32 v[54:55], v[38:39]
	v_mov_b64_e32 v[52:53], v[36:37]
	v_mov_b64_e32 v[50:51], v[34:35]
	v_mov_b64_e32 v[48:49], v[32:33]
	v_mov_b64_e32 v[18:19], v[34:35]
	v_mov_b64_e32 v[20:21], v[36:37]
	v_mov_b64_e32 v[22:23], v[38:39]
	v_mov_b64_e32 v[24:25], v[40:41]
	v_mov_b64_e32 v[26:27], v[42:43]
	v_mov_b64_e32 v[28:29], v[44:45]
	v_mov_b64_e32 v[30:31], v[46:47]
	v_mov_b64_e32 v[2:3], v[34:35]
	v_mov_b64_e32 v[4:5], v[36:37]
	v_mov_b64_e32 v[6:7], v[38:39]
	v_mov_b64_e32 v[8:9], v[40:41]
	v_mov_b64_e32 v[10:11], v[42:43]
	v_mov_b64_e32 v[12:13], v[44:45]
	v_mov_b64_e32 v[14:15], v[46:47]
	s_waitcnt vmcnt(11)
	ds_write_b128 v180, v[96:99]
	s_waitcnt vmcnt(10)
	ds_write_b128 v181, v[100:103]
	s_waitcnt vmcnt(9)
	ds_write_b128 v182, v[136:139] offset:32768
	s_waitcnt vmcnt(8)
	ds_write_b128 v182, v[140:143] offset:40960
	s_waitcnt lgkmcnt(0)
	s_barrier
	v_add_u32_e32 v168, 0x4000, v148
	global_load_dwordx4 v[136:139], v168, s[42:43]
	global_load_dwordx4 v[140:143], v168, s[26:27]
	v_add_u32_e32 v169, 0x4000, v168
	s_mov_b32 s13, 0
	s_mov_b32 s12, 0
	s_mov_b32 s10, 0x3e0293ee
	s_mov_b32 s6, 0x11000
	s_mov_b32 s7, 0
	s_mov_b32 s8, 0x4000
	ds_read_b128 v[236:239], v186 offset:32768
	ds_read_b128 v[240:243], v186 offset:40960
	v_mov_b32_e32 v244, 0
	v_mov_b32_e32 v245, 0
	v_mov_b32_e32 v246, 0
	v_mov_b32_e32 v247, 0
	v_add_u32_e32 v200, s6, v180
	v_add_u32_e32 v201, s6, v181
	ds_write_b128 v200, v[244:247]
	ds_write_b128 v201, v[244:247]
	v_mov_b32_e32 v204, 0
	v_mov_b32_e32 v205, 0
	v_mov_b32_e32 v206, 0
	v_mov_b32_e32 v207, 0
	v_mov_b32_e32 v208, 0
	v_mov_b32_e32 v209, 0
	v_mov_b32_e32 v210, 0
	v_mov_b32_e32 v211, 0
	v_mov_b32_e32 v212, 0
	v_mov_b32_e32 v213, 0
	v_mov_b32_e32 v214, 0
	v_mov_b32_e32 v215, 0
	v_mov_b32_e32 v216, 0
	v_mov_b32_e32 v217, 0
	v_mov_b32_e32 v218, 0
	v_mov_b32_e32 v219, 0
	v_cvt_f32_u32_e32 v64, s13
	v_mov_b32_e32 v165, v164
	v_fma_f32 v64, v172, v64, v179
	v_add_f32_e32 v68, v173, v64
	v_add_f32_e32 v72, v173, v68
	v_add_f32_e32 v76, v173, v72
	v_add_f32_e32 v65, v172, v64
	v_add_f32_e32 v69, v172, v68
	v_add_f32_e32 v73, v172, v72
	v_add_f32_e32 v77, v172, v76
	v_pk_add_f32 v[66:67], v[162:163], v[64:65] op_sel_hi:[1,0]
	v_pk_add_f32 v[70:71], v[162:163], v[68:69] op_sel_hi:[1,0]
	v_pk_add_f32 v[74:75], v[162:163], v[72:73] op_sel_hi:[1,0]
	v_pk_add_f32 v[78:79], v[162:163], v[76:77] op_sel_hi:[1,0]
	v_pk_add_f32 v[82:83], v[164:165], v[66:67]
	v_pk_add_f32 v[80:81], v[166:167], v[64:65]
	v_pk_add_f32 v[86:87], v[164:165], v[70:71]
	v_pk_add_f32 v[84:85], v[164:165], v[68:69]
	v_pk_add_f32 v[90:91], v[164:165], v[74:75]
	v_pk_add_f32 v[88:89], v[164:165], v[72:73]
	v_pk_add_f32 v[94:95], v[164:165], v[78:79]
	v_pk_add_f32 v[92:93], v[164:165], v[76:77]
	s_addk_i32 s13, 0x40
	s_waitcnt lgkmcnt(3)
	v_mfma_f32_32x32x16_bf16 v[64:79], v[236:239], v[104:107], v[64:79]
	ds_read_b128 v[236:239], v187 offset:32768
	s_waitcnt lgkmcnt(3)
	v_mfma_f32_32x32x16_bf16 v[80:95], v[240:243], v[104:107], v[80:95]
	ds_read_b128 v[240:243], v187 offset:40960
	s_waitcnt lgkmcnt(1)
	v_mfma_f32_32x32x16_bf16 v[64:79], v[236:239], v[108:111], v[64:79]
	ds_read_b128 v[236:239], v188 offset:32768
	s_waitcnt lgkmcnt(1)
	v_mfma_f32_32x32x16_bf16 v[80:95], v[240:243], v[108:111], v[80:95]
	ds_read_b128 v[240:243], v188 offset:40960
	s_waitcnt lgkmcnt(1)
	v_mfma_f32_32x32x16_bf16 v[64:79], v[236:239], v[112:115], v[64:79]
	ds_read_b128 v[236:239], v189 offset:32768
	s_waitcnt lgkmcnt(1)
	v_mfma_f32_32x32x16_bf16 v[80:95], v[240:243], v[112:115], v[80:95]
	ds_read_b128 v[240:243], v189 offset:40960
	s_waitcnt lgkmcnt(1)
	v_mfma_f32_32x32x16_bf16 v[64:79], v[236:239], v[116:119], v[64:79]
	v_xor_b32_e32 v186, 0x80, v186
	v_xor_b32_e32 v187, 0x80, v187
	v_xor_b32_e32 v188, 0x80, v188
	v_xor_b32_e32 v189, 0x80, v189
	ds_read_b128 v[236:239], v186 offset:32768
	s_waitcnt lgkmcnt(1)
	v_mfma_f32_32x32x16_bf16 v[80:95], v[240:243], v[116:119], v[80:95]
	ds_read_b128 v[240:243], v186 offset:40960
	s_waitcnt lgkmcnt(1)
	v_mfma_f32_32x32x16_bf16 v[64:79], v[236:239], v[120:123], v[64:79]
	ds_read_b128 v[236:239], v187 offset:32768
	s_waitcnt lgkmcnt(1)
	v_mfma_f32_32x32x16_bf16 v[80:95], v[240:243], v[120:123], v[80:95]
	ds_read_b128 v[240:243], v187 offset:40960
	s_waitcnt lgkmcnt(1)
	v_mfma_f32_32x32x16_bf16 v[64:79], v[236:239], v[124:127], v[64:79]
	ds_read_b128 v[236:239], v188 offset:32768
	s_waitcnt lgkmcnt(1)
	v_mfma_f32_32x32x16_bf16 v[80:95], v[240:243], v[124:127], v[80:95]
	ds_read_b128 v[240:243], v188 offset:40960
	s_waitcnt lgkmcnt(1)
	v_mfma_f32_32x32x16_bf16 v[64:79], v[236:239], v[128:131], v[64:79]
	ds_read_b128 v[236:239], v189 offset:32768
	s_waitcnt lgkmcnt(1)
	v_mfma_f32_32x32x16_bf16 v[80:95], v[240:243], v[128:131], v[80:95]
	ds_read_b128 v[240:243], v189 offset:40960
	s_waitcnt lgkmcnt(1)
	v_mfma_f32_32x32x16_bf16 v[64:79], v[236:239], v[132:135], v[64:79]
	s_waitcnt lgkmcnt(0)
	v_mfma_f32_32x32x16_bf16 v[80:95], v[240:243], v[132:135], v[80:95]
	s_waitcnt vmcnt(0)
	ds_write_b128 v182, v[136:139] offset:49152
	ds_write_b128 v182, v[140:143] offset:57344
	s_waitcnt lgkmcnt(0)
	s_barrier
	.p2alignl 6, 3212836864

.Lat_nre:
	v_xor_b32_e32 v186, 0x80, v186
	v_xor_b32_e32 v187, 0x80, v187
	v_xor_b32_e32 v188, 0x80, v188
	v_xor_b32_e32 v189, 0x80, v189
	ds_read_b128 v[236:239], v186 offset:49152
	ds_read_b128 v[240:243], v186 offset:57344
	v_cvt_f32_u32_e32 v204, s13
	v_mov_b32_e32 v165, v164
	v_fma_f32 v204, v172, v204, v179
	v_add_f32_e32 v208, v173, v204
	v_add_f32_e32 v212, v173, v208
	v_add_f32_e32 v216, v173, v212
	v_add_f32_e32 v205, v172, v204
	v_add_f32_e32 v209, v172, v208
	v_add_f32_e32 v213, v172, v212
	v_add_f32_e32 v217, v172, v216
	v_pk_add_f32 v[206:207], v[162:163], v[204:205] op_sel_hi:[1,0]
	v_pk_add_f32 v[210:211], v[162:163], v[208:209] op_sel_hi:[1,0]
	v_pk_add_f32 v[214:215], v[162:163], v[212:213] op_sel_hi:[1,0]
	v_pk_add_f32 v[218:219], v[162:163], v[216:217] op_sel_hi:[1,0]
	v_pk_add_f32 v[222:223], v[164:165], v[206:207]
	v_pk_add_f32 v[220:221], v[166:167], v[204:205]
	v_pk_add_f32 v[226:227], v[164:165], v[210:211]
	v_pk_add_f32 v[224:225], v[164:165], v[208:209]
	v_pk_add_f32 v[230:231], v[164:165], v[214:215]
	v_pk_add_f32 v[228:229], v[164:165], v[212:213]
	v_pk_add_f32 v[234:235], v[164:165], v[218:219]
	v_pk_add_f32 v[232:233], v[164:165], v[216:217]
	s_addk_i32 s13, 0x40
	v_exp_f32_e32 v80, v80
	s_waitcnt lgkmcnt(1)
	v_mfma_f32_32x32x16_bf16 v[204:219], v[236:239], v[104:107], v[204:219]
	ds_read_b128 v[236:239], v187 offset:49152
	v_exp_f32_e32 v81, v81
	v_pk_add_f32 v[170:171], v[170:171], v[78:79]
	v_exp_f32_e32 v82, v82
	s_waitcnt lgkmcnt(1)
	v_mfma_f32_32x32x16_bf16 v[220:235], v[240:243], v[104:107], v[220:235]
	ds_read_b128 v[240:243], v187 offset:57344
	v_exp_f32_e32 v83, v83
	v_pk_add_f32 v[170:171], v[170:171], v[80:81]
	v_exp_f32_e32 v84, v84
	v_exp_f32_e32 v85, v85
	s_waitcnt lgkmcnt(1)
	v_mfma_f32_32x32x16_bf16 v[204:219], v[236:239], v[108:111], v[204:219]
	ds_read_b128 v[236:239], v188 offset:49152
	v_pk_add_f32 v[170:171], v[170:171], v[82:83]
	v_exp_f32_e32 v86, v86
	v_exp_f32_e32 v87, v87
	s_waitcnt lgkmcnt(1)
	v_mfma_f32_32x32x16_bf16 v[220:235], v[240:243], v[108:111], v[220:235]
	ds_read_b128 v[240:243], v188 offset:57344
	v_pk_add_f32 v[170:171], v[170:171], v[84:85]
	v_exp_f32_e32 v88, v88
	v_exp_f32_e32 v89, v89
	v_pk_add_f32 v[170:171], v[170:171], v[86:87]
	s_waitcnt lgkmcnt(1)
	v_mfma_f32_32x32x16_bf16 v[204:219], v[236:239], v[112:115], v[204:219]
	ds_read_b128 v[236:239], v189 offset:49152
	v_exp_f32_e32 v90, v90
	v_exp_f32_e32 v91, v91
	v_pk_add_f32 v[170:171], v[170:171], v[88:89]
	v_exp_f32_e32 v92, v92
	s_waitcnt lgkmcnt(1)
	v_mfma_f32_32x32x16_bf16 v[220:235], v[240:243], v[112:115], v[220:235]
	ds_read_b128 v[240:243], v189 offset:57344
	v_exp_f32_e32 v93, v93
	v_pk_add_f32 v[170:171], v[170:171], v[90:91]
	v_exp_f32_e32 v94, v94
	s_waitcnt lgkmcnt(1)
	v_mfma_f32_32x32x16_bf16 v[204:219], v[236:239], v[116:119], v[204:219]
	v_xor_b32_e32 v186, 0x80, v186
	v_xor_b32_e32 v187, 0x80, v187
	v_xor_b32_e32 v188, 0x80, v188
	v_xor_b32_e32 v189, 0x80, v189
	ds_read_b128 v[236:239], v186 offset:49152
	v_exp_f32_e32 v95, v95
	v_pk_add_f32 v[170:171], v[170:171], v[92:93]
	s_nop 0
	v_pk_add_f32 v[170:171], v[170:171], v[94:95]
	s_waitcnt lgkmcnt(1)
	v_mfma_f32_32x32x16_bf16 v[220:235], v[240:243], v[116:119], v[220:235]
	ds_read_b128 v[240:243], v186 offset:57344
	v_add_f32_e32 v249, v170, v171
	v_mov_b32_e32 v170, v249
	s_nop 1
	s_waitcnt lgkmcnt(1)
	v_mfma_f32_32x32x16_bf16 v[204:219], v[236:239], v[120:123], v[204:219]
	ds_read_b128 v[236:239], v187 offset:49152
	v_permlane32_swap_b32_e32 v249, v170
	v_cvt_pk_bf16_f32 v64, v64, v65
	v_cvt_pk_bf16_f32 v65, v66, v67
	v_cvt_pk_bf16_f32 v66, v68, v69
	s_waitcnt lgkmcnt(1)
	v_mfma_f32_32x32x16_bf16 v[220:235], v[240:243], v[120:123], v[220:235]
	ds_read_b128 v[240:243], v187 offset:57344
	v_cvt_pk_bf16_f32 v67, v70, v71
	v_cvt_pk_bf16_f32 v68, v72, v73
	v_cvt_pk_bf16_f32 v69, v74, v75
	s_waitcnt lgkmcnt(1)
	v_mfma_f32_32x32x16_bf16 v[204:219], v[236:239], v[124:127], v[204:219]
	ds_read_b128 v[236:239], v188 offset:49152
	v_cvt_pk_bf16_f32 v70, v76, v77
	v_cvt_pk_bf16_f32 v71, v78, v79
	v_cvt_pk_bf16_f32 v72, v80, v81
	v_cvt_pk_bf16_f32 v73, v82, v83
	s_waitcnt lgkmcnt(1)
	v_mfma_f32_32x32x16_bf16 v[220:235], v[240:243], v[124:127], v[220:235]
	ds_read_b128 v[240:243], v188 offset:57344
	v_cvt_pk_bf16_f32 v74, v84, v85
	v_cvt_pk_bf16_f32 v75, v86, v87
	v_cvt_pk_bf16_f32 v76, v88, v89
	s_waitcnt lgkmcnt(1)
	v_mfma_f32_32x32x16_bf16 v[204:219], v[236:239], v[128:131], v[204:219]
	ds_read_b128 v[236:239], v189 offset:49152
	v_cvt_pk_bf16_f32 v77, v90, v91
	v_cvt_pk_bf16_f32 v78, v92, v93
	v_cvt_pk_bf16_f32 v79, v94, v95
	v_permlane32_swap_b32_e32 v64, v66
	s_waitcnt lgkmcnt(1)
	v_mfma_f32_32x32x16_bf16 v[220:235], v[240:243], v[128:131], v[220:235]
	ds_read_b128 v[240:243], v189 offset:57344
	v_permlane32_swap_b32_e32 v65, v67
	v_permlane32_swap_b32_e32 v68, v70
	v_permlane32_swap_b32_e32 v69, v71
	v_permlane32_swap_b32_e32 v72, v74
	s_waitcnt lgkmcnt(1)
	v_mfma_f32_32x32x16_bf16 v[204:219], v[236:239], v[132:135], v[204:219]
	v_permlane32_swap_b32_e32 v73, v75
	v_permlane32_swap_b32_e32 v76, v78
	v_permlane32_swap_b32_e32 v77, v79
	s_waitcnt lgkmcnt(0)
	v_mfma_f32_32x32x16_bf16 v[220:235], v[240:243], v[132:135], v[220:235]
	v_add_f32_e32 v171, v249, v170
	v_fmac_f32_e32 v171, v185, v202
	v_mov_b32_e32 v185, v171
	s_waitcnt vmcnt(0)
	v_add_u32_e32 v200, s8, v180
	v_add_u32_e32 v201, s8, v181
	ds_write_b128 v200, v[96:99]
	ds_write_b128 v201, v[100:103]
	s_and_b64 vcc, exec, s[34:35]
	s_cbranch_vccz .Lat_nwe
	ds_write_b128 v182, v[136:139] offset:32768
	ds_write_b128 v182, v[140:143] offset:40960

.Lat_nro:
	v_xor_b32_e32 v186, 0x80, v186
	v_xor_b32_e32 v187, 0x80, v187
	v_xor_b32_e32 v188, 0x80, v188
	v_xor_b32_e32 v189, 0x80, v189
	ds_read_b128 v[236:239], v186 offset:32768
	ds_read_b128 v[240:243], v186 offset:40960
	v_cvt_f32_u32_e32 v64, s13
	v_mov_b32_e32 v165, v164
	v_fma_f32 v64, v172, v64, v179
	v_add_f32_e32 v68, v173, v64
	v_add_f32_e32 v72, v173, v68
	v_add_f32_e32 v76, v173, v72
	v_add_f32_e32 v65, v172, v64
	v_add_f32_e32 v69, v172, v68
	v_add_f32_e32 v73, v172, v72
	v_add_f32_e32 v77, v172, v76
	v_pk_add_f32 v[66:67], v[162:163], v[64:65] op_sel_hi:[1,0]
	v_pk_add_f32 v[70:71], v[162:163], v[68:69] op_sel_hi:[1,0]
	v_pk_add_f32 v[74:75], v[162:163], v[72:73] op_sel_hi:[1,0]
	v_pk_add_f32 v[78:79], v[162:163], v[76:77] op_sel_hi:[1,0]
	v_pk_add_f32 v[82:83], v[164:165], v[66:67]
	v_pk_add_f32 v[80:81], v[166:167], v[64:65]
	v_pk_add_f32 v[86:87], v[164:165], v[70:71]
	v_pk_add_f32 v[84:85], v[164:165], v[68:69]
	v_pk_add_f32 v[90:91], v[164:165], v[74:75]
	v_pk_add_f32 v[88:89], v[164:165], v[72:73]
	v_pk_add_f32 v[94:95], v[164:165], v[78:79]
	v_pk_add_f32 v[92:93], v[164:165], v[76:77]
	s_addk_i32 s13, 0x40
	v_exp_f32_e32 v220, v220
	s_waitcnt lgkmcnt(1)
	v_mfma_f32_32x32x16_bf16 v[64:79], v[236:239], v[104:107], v[64:79]
	ds_read_b128 v[236:239], v187 offset:32768
	v_exp_f32_e32 v221, v221
	v_pk_add_f32 v[170:171], v[170:171], v[218:219]
	v_exp_f32_e32 v222, v222
	s_waitcnt lgkmcnt(1)
	v_mfma_f32_32x32x16_bf16 v[80:95], v[240:243], v[104:107], v[80:95]
	ds_read_b128 v[240:243], v187 offset:40960
	v_exp_f32_e32 v223, v223
	v_pk_add_f32 v[170:171], v[170:171], v[220:221]
	v_exp_f32_e32 v224, v224
	v_exp_f32_e32 v225, v225
	s_waitcnt lgkmcnt(1)
	v_mfma_f32_32x32x16_bf16 v[64:79], v[236:239], v[108:111], v[64:79]
	ds_read_b128 v[236:239], v188 offset:32768
	v_pk_add_f32 v[170:171], v[170:171], v[222:223]
	v_exp_f32_e32 v226, v226
	v_exp_f32_e32 v227, v227
	s_waitcnt lgkmcnt(1)
	v_mfma_f32_32x32x16_bf16 v[80:95], v[240:243], v[108:111], v[80:95]
	ds_read_b128 v[240:243], v188 offset:40960
	v_pk_add_f32 v[170:171], v[170:171], v[224:225]
	v_exp_f32_e32 v228, v228
	v_exp_f32_e32 v229, v229
	v_pk_add_f32 v[170:171], v[170:171], v[226:227]
	s_waitcnt lgkmcnt(1)
	v_mfma_f32_32x32x16_bf16 v[64:79], v[236:239], v[112:115], v[64:79]
	ds_read_b128 v[236:239], v189 offset:32768
	v_exp_f32_e32 v230, v230
	v_exp_f32_e32 v231, v231
	v_pk_add_f32 v[170:171], v[170:171], v[228:229]
	v_exp_f32_e32 v232, v232
	s_waitcnt lgkmcnt(1)
	v_mfma_f32_32x32x16_bf16 v[80:95], v[240:243], v[112:115], v[80:95]
	ds_read_b128 v[240:243], v189 offset:40960
	v_exp_f32_e32 v233, v233
	v_pk_add_f32 v[170:171], v[170:171], v[230:231]
	v_exp_f32_e32 v234, v234
	s_waitcnt lgkmcnt(1)
	v_mfma_f32_32x32x16_bf16 v[64:79], v[236:239], v[116:119], v[64:79]
	v_xor_b32_e32 v186, 0x80, v186
	v_xor_b32_e32 v187, 0x80, v187
	v_xor_b32_e32 v188, 0x80, v188
	v_xor_b32_e32 v189, 0x80, v189
	ds_read_b128 v[236:239], v186 offset:32768
	v_exp_f32_e32 v235, v235
	v_pk_add_f32 v[170:171], v[170:171], v[232:233]
	s_nop 0
	v_pk_add_f32 v[170:171], v[170:171], v[234:235]
	s_waitcnt lgkmcnt(1)
	v_mfma_f32_32x32x16_bf16 v[80:95], v[240:243], v[116:119], v[80:95]
	ds_read_b128 v[240:243], v186 offset:40960
	v_add_f32_e32 v249, v170, v171
	v_mov_b32_e32 v170, v249
	s_nop 1
	s_waitcnt lgkmcnt(1)
	v_mfma_f32_32x32x16_bf16 v[64:79], v[236:239], v[120:123], v[64:79]
	ds_read_b128 v[236:239], v187 offset:32768
	v_permlane32_swap_b32_e32 v249, v170
	v_cvt_pk_bf16_f32 v204, v204, v205
	v_cvt_pk_bf16_f32 v205, v206, v207
	v_cvt_pk_bf16_f32 v206, v208, v209
	s_waitcnt lgkmcnt(1)
	v_mfma_f32_32x32x16_bf16 v[80:95], v[240:243], v[120:123], v[80:95]
	ds_read_b128 v[240:243], v187 offset:40960
	v_cvt_pk_bf16_f32 v207, v210, v211
	v_cvt_pk_bf16_f32 v208, v212, v213
	v_cvt_pk_bf16_f32 v209, v214, v215
	s_waitcnt lgkmcnt(1)
	v_mfma_f32_32x32x16_bf16 v[64:79], v[236:239], v[124:127], v[64:79]
	ds_read_b128 v[236:239], v188 offset:32768
	v_cvt_pk_bf16_f32 v210, v216, v217
	v_cvt_pk_bf16_f32 v211, v218, v219
	v_cvt_pk_bf16_f32 v212, v220, v221
	v_cvt_pk_bf16_f32 v213, v222, v223
	s_waitcnt lgkmcnt(1)
	v_mfma_f32_32x32x16_bf16 v[80:95], v[240:243], v[124:127], v[80:95]
	ds_read_b128 v[240:243], v188 offset:40960
	v_cvt_pk_bf16_f32 v214, v224, v225
	v_cvt_pk_bf16_f32 v215, v226, v227
	v_cvt_pk_bf16_f32 v216, v228, v229
	s_waitcnt lgkmcnt(1)
	v_mfma_f32_32x32x16_bf16 v[64:79], v[236:239], v[128:131], v[64:79]
	ds_read_b128 v[236:239], v189 offset:32768
	v_cvt_pk_bf16_f32 v217, v230, v231
	v_cvt_pk_bf16_f32 v218, v232, v233
	v_cvt_pk_bf16_f32 v219, v234, v235
	v_permlane32_swap_b32_e32 v204, v206
	s_waitcnt lgkmcnt(1)
	v_mfma_f32_32x32x16_bf16 v[80:95], v[240:243], v[128:131], v[80:95]
	ds_read_b128 v[240:243], v189 offset:40960
	v_permlane32_swap_b32_e32 v205, v207
	v_permlane32_swap_b32_e32 v208, v210
	v_permlane32_swap_b32_e32 v209, v211
	v_permlane32_swap_b32_e32 v212, v214
	s_waitcnt lgkmcnt(1)
	v_mfma_f32_32x32x16_bf16 v[64:79], v[236:239], v[132:135], v[64:79]
	v_permlane32_swap_b32_e32 v213, v215
	v_permlane32_swap_b32_e32 v216, v218
	v_permlane32_swap_b32_e32 v217, v219
	s_waitcnt lgkmcnt(0)
	v_mfma_f32_32x32x16_bf16 v[80:95], v[240:243], v[132:135], v[80:95]
	v_add_f32_e32 v171, v249, v170
	v_fmac_f32_e32 v171, v185, v202
	v_mov_b32_e32 v185, v171
	s_waitcnt vmcnt(0)
	s_and_b64 vcc, exec, s[34:35]
	s_cbranch_vccz .Lat_nwo
	v_add_u32_e32 v200, s8, v180
	v_add_u32_e32 v201, s8, v181
	ds_write_b128 v200, v[96:99]
	ds_write_b128 v201, v[100:103]
	ds_write_b128 v182, v[136:139] offset:49152
	ds_write_b128 v182, v[140:143] offset:57344
